# mlstm_seq chunk loop hand-scheduled: LDS operand reads software-pipelined ahead of MFMAs, DPP reduction, staging moved after barrier
# speedup vs baseline: 1.0121x; 1.0121x over previous
; #define LAS __attribute__((address_space(3)))
; #define MFMA32(a, b, c) __builtin_amdgcn_mfma_f32_32x32x16_bf16((a), (b), (c), 0, 0, 0)
; __device__ __forceinline__ void mlstm_seq(LAS unsigned char* lds, int tid_in, int b, int h, const bf16_t* z1, const bf16_t* z2a, const float* g_hnorm, bf16_t* yb, const unsigned char* ws) {
;     ...
;     ML_PREFETCH(0);
; #pragma nounroll
;     for (int c = 0; c < 64; ++c) {
;         const size_t tok0 = (size_t)b * SEQL + c * 64;
;         const float decay = pdec;
; #pragma unroll
;         for (int i = 0; i < 2; ++i) { *(LAS u32x4*)(Qb + (srow + 32 * i) * QS + sc16 * 16) = pq[i]; *(LAS u32x4*)(KUb + (srow + 32 * i) * US + sc16 * 16) = pk[i]; }
; #pragma unroll
;         for (int i = 0; i < 4; ++i) *(LAS u32x4*)(Vb + (vrow + 16 * i) * VS + vc * 16) = pv[i];
;         *(LAS u32x4*)(SCb + (tid >> 3) * SS + (tid & 7) * 16) = psc;
;         u32x2 zo[2][4];
; #pragma unroll
;         for (int tb = 0; tb < 2; ++tb)
; #pragma unroll
;             for (int g = 0; g < 4; ++g) zo[tb][g] = pzo[tb][g];
;         const float wi0 = pwi0, wi1 = pwi1, wq = pwq, eq = peq, dq0 = pdq, dn = pdn;
;         __syncthreads();
;         if (c + 1 < 64) ML_PREFETCH(c + 1);
;     ...
;                     const LAS unsigned char* p = Qb + (32 * tb + r) * QS + (32 * dkb + 16 * s2 + 4 * hh) * 2;
;                     const u32x2 lo = *(const LAS u32x2*)p, hi = *(const LAS u32x2*)(p + 16);
;                     const u32x4 bq = {lo.x, lo.y, hi.x, hi.y};
;                     Z[tb] = MFMA32(ax, __builtin_bit_cast(bf16x8, bq), Z[tb]);
;                 }
;             }
;         { float f[16]; { float t8[8]; unpack8(*(const LAS u32x4*)(Qb + tq * QS + part * 32), t8);
; #pragma unroll
;               for (int e = 0; e < 8; ++e) f[e] = t8[e];
;               unpack8(*(const LAS u32x4*)(Qb + tq * QS + part * 32 + 16), t8);
; #pragma unroll
;               for (int e = 0; e < 8; ++e) f[8 + e] = t8[e]; }
;           float dq = 0.f;
; #pragma unroll
;           for (int j = 0; j < 4; ++j) { const f32x4 n4 = *(const LAS f32x4*)(NV + 16 * part + 4 * j); dq += (f[4 * j] * n4[0] + f[4 * j + 1] * n4[1]) + (f[4 * j + 2] * n4[2] + f[4 * j + 3] * n4[3]); }
.Lml_first:
	v_mov_b32_e32 v250, v134
	v_mov_b32_e32 v251, v135
	ds_write_b128 v0, v[98:101]
	ds_write_b128 v206, v[102:105] offset:17408
	ds_write_b128 v0, v[106:109] offset:8704
	ds_write_b128 v206, v[110:113] offset:27648
	ds_write_b128 v202, v[114:117] offset:37888
	ds_write_b128 v202, v[118:121] offset:47104
	ds_write_b128 v202, v[122:125] offset:56320
	ds_write_b128 v203, v[126:129] offset:27648
	ds_write_b128 v207, v[130:133]
	s_waitcnt lgkmcnt(0)
	s_barrier
.Lml_loop:
	v_add_u32_e32 v144, 0x2000, v208
	ds_read2_b64 v[146:149], v208 offset1:2
	ds_read2_b64 v[222:225], v144 offset0:64 offset1:66
	ds_read2_b64 v[230:233], v208 offset0:4 offset1:6
	ds_read2_b64 v[234:237], v144 offset0:68 offset1:70
	ds_read_b128 v[242:245], v209
	ds_read_b128 v[246:249], v209 offset:16
	ds_read_b128 v[238:241], v165
	s_cmp_eq_u32 s14, 1
	s_cbranch_scc1 .Lml_nopf
	v_lshl_add_u64 v[66:67], s[66:67], 0, v[176:177]
	v_add_co_u32_e32 v68, vcc, 0x6068000, v66
	s_add_u32 s12, s66, s8
	s_nop 0
	v_addc_co_u32_e32 v69, vcc, 0, v67, vcc
	global_load_dwordx4 v[98:101], v[68:69], off offset:2560
	v_add_co_u32_e32 v68, vcc, 0x6069000, v66
	s_addc_u32 s13, s67, s9
	s_nop 0
	v_addc_co_u32_e32 v69, vcc, 0, v67, vcc
	global_load_dwordx4 v[102:105], v[68:69], off offset:512
	v_add_co_u32_e32 v68, vcc, 0x609c000, v66
	global_load_dword v215, v1, s[12:13]
	s_nop 0
	v_addc_co_u32_e32 v69, vcc, 0, v67, vcc
	v_add_co_u32_e32 v66, vcc, 0x609d000, v66
	global_load_dwordx4 v[106:109], v[68:69], off offset:2560
	s_nop 0
	v_addc_co_u32_e32 v67, vcc, 0, v67, vcc
	global_load_dwordx4 v[110:113], v[66:67], off offset:512
	v_lshl_add_u64 v[66:67], s[66:67], 0, v[172:173]
	v_add_co_u32_e32 v68, vcc, 0x10880000, v66
	v_mov_b32_e32 v219, v216
	s_nop 0
	v_addc_co_u32_e32 v69, vcc, 0, v67, vcc
	global_load_dwordx4 v[114:117], v[68:69], off
	v_add_co_u32_e32 v68, vcc, 0x108a0000, v66
	s_nop 1
	v_addc_co_u32_e32 v69, vcc, 0, v67, vcc
	global_load_dwordx4 v[118:121], v[68:69], off
	v_add_co_u32_e32 v68, vcc, 0x108c0000, v66
	s_nop 1
	v_addc_co_u32_e32 v69, vcc, 0, v67, vcc
	v_add_co_u32_e32 v66, vcc, 0x108e0000, v66
	global_load_dwordx4 v[122:125], v[68:69], off
	s_nop 0
	v_addc_co_u32_e32 v67, vcc, 0, v67, vcc
	global_load_dwordx4 v[126:129], v[66:67], off
	v_lshl_add_u64 v[66:67], s[66:67], 0, v[162:163]
	global_load_dwordx4 v[130:133], v[66:67], off
	v_lshl_add_u64 v[66:67], s[66:67], 0, v[150:151]
	v_add_co_u32_e32 v68, vcc, 0x10881000, v66
	s_nop 1
	v_addc_co_u32_e32 v69, vcc, 0, v67, vcc
	v_add_co_u32_e32 v66, vcc, 0x108c1000, v66
	global_load_dwordx2 v[182:183], v[68:69], off
	global_load_dwordx2 v[184:185], v[68:69], off offset:16
	global_load_dwordx2 v[186:187], v[68:69], off offset:32
	global_load_dwordx2 v[188:189], v[68:69], off offset:48
	v_addc_co_u32_e32 v67, vcc, 0, v67, vcc
	global_load_dwordx2 v[190:191], v[66:67], off
	global_load_dwordx2 v[192:193], v[66:67], off offset:16
	global_load_dwordx2 v[194:195], v[66:67], off offset:32
	global_load_dwordx2 v[196:197], v[66:67], off offset:48
	v_lshl_add_u64 v[66:67], s[66:67], 0, v[170:171]
	v_add_co_u32_e32 v68, vcc, 0x1dc80000, v66
	s_nop 1
	v_addc_co_u32_e32 v69, vcc, 0, v67, vcc
	v_add_co_u32_e32 v66, vcc, 0x1de80000, v66
	global_load_dword v217, v[68:69], off offset:2048
	s_nop 0
	v_addc_co_u32_e32 v67, vcc, 0, v67, vcc
	global_load_dword v218, v[66:67], off offset:2048
	s_and_saveexec_b64 s[12:13], s[40:41]
	s_cbranch_execz .LBB0_86
	v_lshl_add_u64 v[66:67], s[66:67], 0, v[160:161]
	global_load_dword v219, v[66:67], off

; #define LAS __attribute__((address_space(3)))
; #define MFMA32(a, b, c) __builtin_amdgcn_mfma_f32_32x32x16_bf16((a), (b), (c), 0, 0, 0)
; __device__ __forceinline__ s16x4 trread(const LAS unsigned char* p) { return __builtin_bit_cast(s16x4, __builtin_amdgcn_ds_read_tr16_b64_v4i16((LAS v4i16_t*)p)); }
; __device__ __forceinline__ bf16x8 cat44(s16x4 lo, s16x4 hi) { return (bf16x8){lo[0], lo[1], lo[2], lo[3], hi[0], hi[1], hi[2], hi[3]}; }
; __device__ __forceinline__ void mlstm_seq(LAS unsigned char* lds, int tid_in, int b, int h, const bf16_t* z1, const bf16_t* z2a, const float* g_hnorm, bf16_t* yb, const unsigned char* ws) {
;     ...
; #pragma unroll
;         for (int dkb = 0; dkb < 4; ++dkb)
; #pragma unroll
;             for (int s2 = 0; s2 < 2; ++s2) {
;                 const bf16x8 ax = packacc8(X[dkb], 8 * s2);
; #pragma unroll
;                 for (int tb = 0; tb < 2; ++tb) {
;                     const LAS unsigned char* p = Qb + (32 * tb + r) * QS + (32 * dkb + 16 * s2 + 4 * hh) * 2;
;                     const u32x2 lo = *(const LAS u32x2*)p, hi = *(const LAS u32x2*)(p + 16);
;                     const u32x4 bq = {lo.x, lo.y, hi.x, hi.y};
;                     Z[tb] = MFMA32(ax, __builtin_bit_cast(bf16x8, bq), Z[tb]);
;                 }
;             }
;         { float f[16]; { float t8[8]; unpack8(*(const LAS u32x4*)(Qb + tq * QS + part * 32), t8);
; #pragma unroll
;               for (int e = 0; e < 8; ++e) f[e] = t8[e];
;               unpack8(*(const LAS u32x4*)(Qb + tq * QS + part * 32 + 16), t8);
; #pragma unroll
;               for (int e = 0; e < 8; ++e) f[8 + e] = t8[e]; }
;           float dq = 0.f;
; #pragma unroll
;           for (int j = 0; j < 4; ++j) { const f32x4 n4 = *(const LAS f32x4*)(NV + 16 * part + 4 * j); dq += (f[4 * j] * n4[0] + f[4 * j + 1] * n4[1]) + (f[4 * j + 2] * n4[2] + f[4 * j + 3] * n4[3]); }
;           dq += __shfl_xor(dq, 1); dq += __shfl_xor(dq, 2); dq += __shfl_xor(dq, 4);
;           if (part == 0) INV[tq] = 1.f / fmaxf(fabsf(dq + dq0), eq); }
;         bf16x8 vf[4];
; #pragma unroll
;         for (int ks = 0; ks < 4; ++ks) {
;             const LAS unsigned char* p = Vb + (16 * ks + 8 * hh + q4) * VS + (32 * wid + 16 * (g4 & 1) + 4 * p4) * 2;
;             vf[ks] = cat44(trread(p), trread(p + 4 * VS));
;         }
.Lml_nopf:
	v_cvt_pk_bf16_f32 v136, v2, v3
	v_cvt_pk_bf16_f32 v137, v4, v5
	v_cvt_pk_bf16_f32 v138, v6, v7
	v_cvt_pk_bf16_f32 v139, v8, v9
	s_nop 0
	s_waitcnt lgkmcnt(6)
	v_mfma_f32_32x32x16_bf16 v[82:97], v[136:139], v[146:149], 0
	ds_read2_b64 v[146:149], v208 offset0:8 offset1:10
	v_cvt_pk_bf16_f32 v140, v10, v11
	v_cvt_pk_bf16_f32 v141, v12, v13
	v_cvt_pk_bf16_f32 v142, v14, v15
	v_cvt_pk_bf16_f32 v143, v16, v17
	s_waitcnt lgkmcnt(6)
	v_mfma_f32_32x32x16_bf16 v[66:81], v[136:139], v[222:225], 0
	ds_read2_b64 v[222:225], v144 offset0:72 offset1:74
	s_waitcnt lgkmcnt(2)
	v_lshlrev_b32_e32 v134, 16, v242
	v_and_b32_e32 v135, 0xffff0000, v242
	v_lshlrev_b32_e32 v226, 16, v243
	v_and_b32_e32 v227, 0xffff0000, v243
	v_mul_f32_e32 v135, v239, v135
	v_mul_f32_e32 v227, v241, v227
	v_fmac_f32_e32 v135, v238, v134
	v_fmac_f32_e32 v227, v240, v226
	ds_read_b128 v[238:241], v165 offset:16
	v_add_f32_e32 v135, v135, v227
	v_add_f32_e32 v229, 0, v135
	v_mfma_f32_32x32x16_bf16 v[82:97], v[140:143], v[230:233], v[82:97]
	ds_read2_b64 v[230:233], v208 offset0:12 offset1:14
	v_cvt_pk_bf16_f32 v136, v18, v19
	v_cvt_pk_bf16_f32 v137, v20, v21
	v_cvt_pk_bf16_f32 v138, v22, v23
	v_cvt_pk_bf16_f32 v139, v24, v25
	v_mfma_f32_32x32x16_bf16 v[66:81], v[140:143], v[234:237], v[66:81]
	ds_read2_b64 v[234:237], v144 offset0:76 offset1:78
	s_waitcnt lgkmcnt(4)
	v_mfma_f32_32x32x16_bf16 v[82:97], v[136:139], v[146:149], v[82:97]
	ds_read2_b64 v[146:149], v208 offset0:16 offset1:18
	v_cvt_pk_bf16_f32 v140, v26, v27
	v_cvt_pk_bf16_f32 v141, v28, v29
	v_cvt_pk_bf16_f32 v142, v30, v31
	v_cvt_pk_bf16_f32 v143, v32, v33
	s_waitcnt lgkmcnt(4)
	v_mfma_f32_32x32x16_bf16 v[66:81], v[136:139], v[222:225], v[66:81]
	ds_read2_b64 v[222:225], v144 offset0:80 offset1:82
	s_waitcnt lgkmcnt(4)
	v_lshlrev_b32_e32 v134, 16, v244
	v_and_b32_e32 v135, 0xffff0000, v244
	v_lshlrev_b32_e32 v226, 16, v245
	v_and_b32_e32 v227, 0xffff0000, v245
	v_mul_f32_e32 v135, v239, v135
	v_mul_f32_e32 v227, v241, v227
	v_fmac_f32_e32 v135, v238, v134
	v_fmac_f32_e32 v227, v240, v226
	ds_read_b128 v[238:241], v165 offset:32
	v_add_f32_e32 v135, v135, v227
	v_add_f32_e32 v229, v229, v135
	s_waitcnt lgkmcnt(4)
	v_mfma_f32_32x32x16_bf16 v[82:97], v[140:143], v[230:233], v[82:97]
	ds_read2_b64 v[230:233], v208 offset0:20 offset1:22
	v_cvt_pk_bf16_f32 v136, v34, v35
	v_cvt_pk_bf16_f32 v137, v36, v37
	v_cvt_pk_bf16_f32 v138, v38, v39
	v_cvt_pk_bf16_f32 v139, v40, v41
	s_waitcnt lgkmcnt(4)
	v_mfma_f32_32x32x16_bf16 v[66:81], v[140:143], v[234:237], v[66:81]
	ds_read2_b64 v[234:237], v144 offset0:84 offset1:86
	s_waitcnt lgkmcnt(4)
	v_mfma_f32_32x32x16_bf16 v[82:97], v[136:139], v[146:149], v[82:97]
	ds_read2_b64 v[146:149], v208 offset0:24 offset1:26
	v_cvt_pk_bf16_f32 v140, v42, v43
	v_cvt_pk_bf16_f32 v141, v44, v45
	v_cvt_pk_bf16_f32 v142, v46, v47
	v_cvt_pk_bf16_f32 v143, v48, v49
	s_waitcnt lgkmcnt(4)
	v_mfma_f32_32x32x16_bf16 v[66:81], v[136:139], v[222:225], v[66:81]
	ds_read2_b64 v[222:225], v144 offset0:88 offset1:90
	s_waitcnt lgkmcnt(4)
	v_lshlrev_b32_e32 v134, 16, v246
	v_and_b32_e32 v135, 0xffff0000, v246
	v_lshlrev_b32_e32 v226, 16, v247
	v_and_b32_e32 v227, 0xffff0000, v247
	v_mul_f32_e32 v135, v239, v135
	v_mul_f32_e32 v227, v241, v227
	v_fmac_f32_e32 v135, v238, v134
	v_fmac_f32_e32 v227, v240, v226
	ds_read_b128 v[238:241], v165 offset:48
	v_add_f32_e32 v135, v135, v227
	v_add_f32_e32 v229, v229, v135
	s_waitcnt lgkmcnt(4)
	v_mfma_f32_32x32x16_bf16 v[82:97], v[140:143], v[230:233], v[82:97]
	ds_read2_b64 v[230:233], v208 offset0:28 offset1:30
	v_cvt_pk_bf16_f32 v136, v50, v51
	v_cvt_pk_bf16_f32 v137, v52, v53
	v_cvt_pk_bf16_f32 v138, v54, v55
	v_cvt_pk_bf16_f32 v139, v56, v57
	s_waitcnt lgkmcnt(4)
	v_mfma_f32_32x32x16_bf16 v[66:81], v[140:143], v[234:237], v[66:81]
	ds_read2_b64 v[234:237], v144 offset0:92 offset1:94
	s_waitcnt lgkmcnt(4)
	v_mfma_f32_32x32x16_bf16 v[82:97], v[136:139], v[146:149], v[82:97]
	v_cvt_pk_bf16_f32 v140, v58, v59
	v_cvt_pk_bf16_f32 v141, v60, v61
	v_cvt_pk_bf16_f32 v142, v62, v63
	v_cvt_pk_bf16_f32 v143, v64, v65
	s_waitcnt lgkmcnt(3)
	v_mfma_f32_32x32x16_bf16 v[66:81], v[136:139], v[222:225], v[66:81]
	s_waitcnt lgkmcnt(2)
	v_lshlrev_b32_e32 v134, 16, v248
	v_and_b32_e32 v135, 0xffff0000, v248
	v_lshlrev_b32_e32 v226, 16, v249
	v_and_b32_e32 v227, 0xffff0000, v249
	v_mul_f32_e32 v135, v239, v135
	v_mul_f32_e32 v227, v241, v227
	v_fmac_f32_e32 v135, v238, v134
	v_fmac_f32_e32 v227, v240, v226
	v_add_f32_e32 v135, v135, v227
	v_add_f32_e32 v229, v229, v135
	s_waitcnt lgkmcnt(1)
	v_mfma_f32_32x32x16_bf16 v[82:97], v[140:143], v[230:233], v[82:97]
	s_waitcnt lgkmcnt(0)
	v_mfma_f32_32x32x16_bf16 v[66:81], v[140:143], v[234:237], v[66:81]
	v_add_f32_dpp v229, v229, v229 quad_perm:[1,0,3,2] row_mask:0xf bank_mask:0xf
	ds_read_b64_tr_b16 v[146:147], v210 offset:37888
	ds_read_b64_tr_b16 v[148:149], v210 offset:40192
	ds_read_b128 v[222:225], v212
	v_add_f32_dpp v229, v229, v229 quad_perm:[2,3,0,1] row_mask:0xf bank_mask:0xf
	ds_read_b64_tr_b16 v[140:141], v210 offset:47104
	ds_read_b64_tr_b16 v[142:143], v210 offset:49408
	ds_read_b128 v[230:233], v212 offset:32
	ds_read_b64_tr_b16 v[136:137], v210 offset:56320
	ds_read_b64_tr_b16 v[138:139], v210 offset:58624
	ds_read_b128 v[234:237], v212 offset:64
	ds_read_b64_tr_b16 v[242:243], v211 offset:56320
	ds_read_b64_tr_b16 v[244:245], v211 offset:58624
	ds_read_b128 v[238:241], v212 offset:96
	ds_read_b128 v[246:249], v212 offset:4608
	v_add_f32_dpp v229, v229, v229 row_half_mirror row_mask:0xf bank_mask:0xf
	s_and_saveexec_b64 s[12:13], s[42:43]
	s_cbranch_execz .Lml_dskip
	v_add_f32_e32 v135, v251, v229
	v_max_f32_e32 v134, v250, v250
	v_max_f32_e64 v134, |v135|, v134
	v_div_scale_f32 v135, s[16:17], v134, v134, 1.0
	v_rcp_f32_e32 v226, v135
	s_nop 0
	v_fma_f32 v227, -v135, v226, 1.0
	v_fmac_f32_e32 v226, v227, v226
	v_div_scale_f32 v227, vcc, 1.0, v134, 1.0
	v_mul_f32_e32 v145, v227, v226
	v_fma_f32 v229, -v135, v145, v227
	v_fmac_f32_e32 v145, v229, v226
	v_fma_f32 v135, -v135, v145, v227
	v_div_fmas_f32 v135, v135, v226, v145
	v_div_fixup_f32 v134, v135, v134, 1.0
	ds_write_b32 v198, v134
; #define LAS __attribute__((address_space(3)))
; #define MFMA32(a, b, c) __builtin_amdgcn_mfma_f32_32x32x16_bf16((a), (b), (c), 0, 0, 0)
; __device__ __forceinline__ s16x4 trread(const LAS unsigned char* p) { return __builtin_bit_cast(s16x4, __builtin_amdgcn_ds_read_tr16_b64_v4i16((LAS v4i16_t*)p)); }
; __device__ __forceinline__ bf16x8 cat44(s16x4 lo, s16x4 hi) { return (bf16x8){lo[0], lo[1], lo[2], lo[3], hi[0], hi[1], hi[2], hi[3]}; }
; __device__ __forceinline__ void mlstm_seq(LAS unsigned char* lds, int tid_in, int b, int h, const bf16_t* z1, const bf16_t* z2a, const float* g_hnorm, bf16_t* yb, const unsigned char* ws) {
;     ...
; #pragma unroll
;         for (int tb = 0; tb < 2; ++tb)
; #pragma unroll
;             for (int ks = 0; ks < 4; ++ks) {
;                 const bf16x8 bs = *(const LAS bf16x8*)(SCb + (32 * tb + r) * SS + (16 * ks + 8 * hh) * 2);
;                 Z[tb] = MFMA32(vf[ks], bs, Z[tb]);
;             }
;         { float p0 = 0.f, p1 = 0.f;
; #pragma unroll
;           for (int i = 0; i < 16; ++i) { p0 += Z[0][i] * Z[0][i]; p1 += Z[1][i] * Z[1][i]; }
;           p0 += __shfl_xor(p0, 32); p1 += __shfl_xor(p1, 32);
;           if (hh == 0) { PR[r * 8 + wid] = p0; PR[(32 + r) * 8 + wid] = p1; } }
; #pragma unroll
;         for (int dkb = 0; dkb < 4; ++dkb) {
; #pragma unroll
;             for (int i = 0; i < 16; ++i) X[dkb][i] *= decay;
; #pragma unroll
;             for (int ks = 0; ks < 4; ++ks) {
;                 const LAS unsigned char* p = KUb + (16 * ks + 8 * hh + q4) * US + (32 * dkb + 16 * (g4 & 1) + 4 * p4) * 2;
;                 X[dkb] = MFMA32(cat44(trread(p), trread(p + 4 * US)), vf[ks], X[dkb]);
;             }
.Lml_dskip:
	s_or_b64 exec, exec, s[12:13]
	v_xor_b32_e32 v144, 32, v220
	v_lshlrev_b32_e32 v144, 2, v144
	s_nop 1
	s_waitcnt lgkmcnt(10)
	v_mfma_f32_32x32x16_bf16 v[82:97], v[146:149], v[222:225], v[82:97]
	ds_read_b128 v[222:225], v212 offset:4640
	s_waitcnt lgkmcnt(8)
	v_mfma_f32_32x32x16_bf16 v[82:97], v[140:143], v[230:233], v[82:97]
	ds_read_b128 v[230:233], v212 offset:4672
	s_waitcnt lgkmcnt(6)
	v_mfma_f32_32x32x16_bf16 v[82:97], v[136:139], v[234:237], v[82:97]
	ds_read_b128 v[234:237], v212 offset:4704
	s_waitcnt lgkmcnt(4)
	v_mfma_f32_32x32x16_bf16 v[82:97], v[242:245], v[238:241], v[82:97]
	ds_read_b64_tr_b16 v[238:239], v213 offset:17408
	ds_read_b64_tr_b16 v[240:241], v213 offset:18688
	s_waitcnt lgkmcnt(5)
	v_mfma_f32_32x32x16_bf16 v[66:81], v[146:149], v[246:249], v[66:81]
	ds_read_b64_tr_b16 v[246:247], v213 offset:22528
	ds_read_b64_tr_b16 v[248:249], v213 offset:23808
	v_pk_mul_f32 v[2:3], v[2:3], v[164:165] op_sel_hi:[1,0]
	v_pk_mul_f32 v[4:5], v[4:5], v[164:165] op_sel_hi:[1,0]
	v_pk_mul_f32 v[6:7], v[6:7], v[164:165] op_sel_hi:[1,0]
	v_pk_mul_f32 v[8:9], v[8:9], v[164:165] op_sel_hi:[1,0]
	s_waitcnt lgkmcnt(6)
	v_mfma_f32_32x32x16_bf16 v[66:81], v[140:143], v[222:225], v[66:81]
	ds_read_b64_tr_b16 v[222:223], v213 offset:27648
	ds_read_b64_tr_b16 v[224:225], v213 offset:28928
	v_pk_mul_f32 v[10:11], v[10:11], v[164:165] op_sel_hi:[1,0]
	v_pk_mul_f32 v[12:13], v[12:13], v[164:165] op_sel_hi:[1,0]
	v_pk_mul_f32 v[14:15], v[14:15], v[164:165] op_sel_hi:[1,0]
	v_pk_mul_f32 v[16:17], v[16:17], v[164:165] op_sel_hi:[1,0]
	s_waitcnt lgkmcnt(7)
	v_mfma_f32_32x32x16_bf16 v[66:81], v[136:139], v[230:233], v[66:81]
	ds_read_b64_tr_b16 v[230:231], v213 offset:32768
	ds_read_b64_tr_b16 v[232:233], v213 offset:34048
	s_waitcnt lgkmcnt(8)
	v_mfma_f32_32x32x16_bf16 v[66:81], v[242:245], v[234:237], v[66:81]
	ds_read_b64_tr_b16 v[234:235], v213 offset:17472
	ds_read_b64_tr_b16 v[236:237], v213 offset:18752
	s_waitcnt lgkmcnt(8)
	v_mfma_f32_32x32x16_bf16 v[2:17], v[238:241], v[146:149], v[2:17]
	ds_read_b64_tr_b16 v[238:239], v213 offset:22592
	ds_read_b64_tr_b16 v[240:241], v213 offset:23872
	v_mul_f32_e32 v134, v82, v82
	v_fmac_f32_e32 v134, v83, v83
	v_fmac_f32_e32 v134, v84, v84
	v_fmac_f32_e32 v134, v85, v85
	v_fmac_f32_e32 v134, v86, v86
	v_fmac_f32_e32 v134, v87, v87
	v_pk_mul_f32 v[18:19], v[18:19], v[164:165] op_sel_hi:[1,0]
	v_pk_mul_f32 v[20:21], v[20:21], v[164:165] op_sel_hi:[1,0]
	s_waitcnt lgkmcnt(8)
	v_mfma_f32_32x32x16_bf16 v[2:17], v[246:249], v[140:143], v[2:17]
	ds_read_b64_tr_b16 v[246:247], v213 offset:27712
	ds_read_b64_tr_b16 v[248:249], v213 offset:28992
	v_fmac_f32_e32 v134, v88, v88
	v_fmac_f32_e32 v134, v89, v89
	v_fmac_f32_e32 v134, v90, v90
	v_fmac_f32_e32 v134, v91, v91
	v_fmac_f32_e32 v134, v92, v92
	v_fmac_f32_e32 v134, v93, v93
	v_pk_mul_f32 v[22:23], v[22:23], v[164:165] op_sel_hi:[1,0]
	v_pk_mul_f32 v[24:25], v[24:25], v[164:165] op_sel_hi:[1,0]
	v_pk_mul_f32 v[26:27], v[26:27], v[164:165] op_sel_hi:[1,0]
	s_waitcnt lgkmcnt(8)
	v_mfma_f32_32x32x16_bf16 v[2:17], v[222:225], v[136:139], v[2:17]
	ds_read_b64_tr_b16 v[222:223], v213 offset:32832
	ds_read_b64_tr_b16 v[224:225], v213 offset:34112
	v_fmac_f32_e32 v134, v94, v94
	v_fmac_f32_e32 v134, v95, v95
	v_fmac_f32_e32 v134, v96, v96
	v_fmac_f32_e32 v134, v97, v97
	v_pk_mul_f32 v[28:29], v[28:29], v[164:165] op_sel_hi:[1,0]
	v_pk_mul_f32 v[30:31], v[30:31], v[164:165] op_sel_hi:[1,0]
	v_pk_mul_f32 v[32:33], v[32:33], v[164:165] op_sel_hi:[1,0]
	s_waitcnt lgkmcnt(8)
	v_mfma_f32_32x32x16_bf16 v[2:17], v[230:233], v[242:245], v[2:17]
	ds_read_b64_tr_b16 v[230:231], v213 offset:17536
	ds_read_b64_tr_b16 v[232:233], v213 offset:18816
	v_mul_f32_e32 v135, v66, v66
	v_fmac_f32_e32 v135, v67, v67
	v_fmac_f32_e32 v135, v68, v68
	v_fmac_f32_e32 v135, v69, v69
	v_fmac_f32_e32 v135, v70, v70
	v_fmac_f32_e32 v135, v71, v71
	s_waitcnt lgkmcnt(8)
	v_mfma_f32_32x32x16_bf16 v[18:33], v[234:237], v[146:149], v[18:33]
	ds_read_b64_tr_b16 v[234:235], v213 offset:22656
	ds_read_b64_tr_b16 v[236:237], v213 offset:23936
	v_fmac_f32_e32 v135, v72, v72
	v_fmac_f32_e32 v135, v73, v73
	v_fmac_f32_e32 v135, v74, v74
	v_fmac_f32_e32 v135, v75, v75
	v_fmac_f32_e32 v135, v76, v76
	v_pk_mul_f32 v[34:35], v[34:35], v[164:165] op_sel_hi:[1,0]
	v_pk_mul_f32 v[36:37], v[36:37], v[164:165] op_sel_hi:[1,0]
	s_waitcnt lgkmcnt(8)
	v_mfma_f32_32x32x16_bf16 v[18:33], v[238:241], v[140:143], v[18:33]
	ds_read_b64_tr_b16 v[238:239], v213 offset:27776
	ds_read_b64_tr_b16 v[240:241], v213 offset:29056
	v_fmac_f32_e32 v135, v77, v77
	v_fmac_f32_e32 v135, v78, v78
	v_fmac_f32_e32 v135, v79, v79
	v_fmac_f32_e32 v135, v80, v80
	v_fmac_f32_e32 v135, v81, v81
	v_pk_mul_f32 v[38:39], v[38:39], v[164:165] op_sel_hi:[1,0]
	v_pk_mul_f32 v[40:41], v[40:41], v[164:165] op_sel_hi:[1,0]
	v_pk_mul_f32 v[42:43], v[42:43], v[164:165] op_sel_hi:[1,0]
	s_waitcnt lgkmcnt(8)
	v_mfma_f32_32x32x16_bf16 v[18:33], v[246:249], v[136:139], v[18:33]
	ds_read_b64_tr_b16 v[246:247], v213 offset:32896
	ds_read_b64_tr_b16 v[248:249], v213 offset:34176
	ds_bpermute_b32 v226, v144, v134
	ds_bpermute_b32 v227, v144, v135
	v_pk_mul_f32 v[44:45], v[44:45], v[164:165] op_sel_hi:[1,0]
	v_pk_mul_f32 v[46:47], v[46:47], v[164:165] op_sel_hi:[1,0]
	v_pk_mul_f32 v[48:49], v[48:49], v[164:165] op_sel_hi:[1,0]
	s_waitcnt lgkmcnt(10)
	v_mfma_f32_32x32x16_bf16 v[18:33], v[222:225], v[242:245], v[18:33]
	ds_read_b64_tr_b16 v[222:223], v213 offset:17600
	ds_read_b64_tr_b16 v[224:225], v213 offset:18880
	v_pk_mul_f32 v[50:51], v[50:51], v[164:165] op_sel_hi:[1,0]
	v_pk_mul_f32 v[52:53], v[52:53], v[164:165] op_sel_hi:[1,0]
	v_pk_mul_f32 v[54:55], v[54:55], v[164:165] op_sel_hi:[1,0]
	s_waitcnt lgkmcnt(10)
	v_mfma_f32_32x32x16_bf16 v[34:49], v[230:233], v[146:149], v[34:49]
	ds_read_b64_tr_b16 v[230:231], v213 offset:22720
	ds_read_b64_tr_b16 v[232:233], v213 offset:24000
	v_pk_mul_f32 v[56:57], v[56:57], v[164:165] op_sel_hi:[1,0]
	v_pk_mul_f32 v[58:59], v[58:59], v[164:165] op_sel_hi:[1,0]
	v_pk_mul_f32 v[60:61], v[60:61], v[164:165] op_sel_hi:[1,0]
	s_waitcnt lgkmcnt(10)
	v_mfma_f32_32x32x16_bf16 v[34:49], v[234:237], v[140:143], v[34:49]
	ds_read_b64_tr_b16 v[234:235], v213 offset:27840
	ds_read_b64_tr_b16 v[236:237], v213 offset:29120
	v_pk_mul_f32 v[62:63], v[62:63], v[164:165] op_sel_hi:[1,0]
	v_pk_mul_f32 v[64:65], v[64:65], v[164:165] op_sel_hi:[1,0]
	s_waitcnt lgkmcnt(10)
	v_mfma_f32_32x32x16_bf16 v[34:49], v[238:241], v[136:139], v[34:49]
	ds_read_b64_tr_b16 v[238:239], v213 offset:32960
	ds_read_b64_tr_b16 v[240:241], v213 offset:34240
	s_waitcnt lgkmcnt(8)
	s_and_saveexec_b64 s[12:13], s[44:45]
	s_cbranch_execz .Lml_prskip
	v_add_f32_e32 v135, v135, v227
	v_add_f32_e32 v134, v134, v226
	ds_write2st64_b32 v200, v134, v135 offset1:4
; #define LAS __attribute__((address_space(3)))
; #define LDS_WAIT() asm volatile("s_waitcnt lgkmcnt(0)" ::: "memory")
; #define MFMA32(a, b, c) __builtin_amdgcn_mfma_f32_32x32x16_bf16((a), (b), (c), 0, 0, 0)
; __device__ __forceinline__ s16x4 trread(const LAS unsigned char* p) { return __builtin_bit_cast(s16x4, __builtin_amdgcn_ds_read_tr16_b64_v4i16((LAS v4i16_t*)p)); }
; __device__ __forceinline__ bf16x8 cat44(s16x4 lo, s16x4 hi) { return (bf16x8){lo[0], lo[1], lo[2], lo[3], hi[0], hi[1], hi[2], hi[3]}; }
; __device__ __forceinline__ void mlstm_seq(LAS unsigned char* lds, int tid_in, int b, int h, const bf16_t* z1, const bf16_t* z2a, const float* g_hnorm, bf16_t* yb, const unsigned char* ws) {
;     ...
;         for (int i = 0; i < 2; ++i) { *(LAS u32x4*)(Qb + (srow + 32 * i) * QS + sc16 * 16) = pq[i]; *(LAS u32x4*)(KUb + (srow + 32 * i) * US + sc16 * 16) = pk[i]; }
; #pragma unroll
;         for (int i = 0; i < 4; ++i) *(LAS u32x4*)(Vb + (vrow + 16 * i) * VS + vc * 16) = pv[i];
;         *(LAS u32x4*)(SCb + (tid >> 3) * SS + (tid & 7) * 16) = psc;
;     ...
;                 X[dkb] = MFMA32(cat44(trread(p), trread(p + 4 * US)), vf[ks], X[dkb]);
;             }
;         }
;         LDS_WAIT(); __builtin_amdgcn_s_barrier(); asm volatile("" ::: "memory");
;         if (tid < 128) NV[tid] = decay * NV[tid] + dn;
; #pragma unroll
;         for (int tb = 0; tb < 2; ++tb) {
;             const int t = 32 * tb + r;
;             const float inv = INV[t];
;             const f32x4 pa = *(const LAS f32x4*)(PR + t * 8), pb = *(const LAS f32x4*)(PR + t * 8 + 4);
.Lml_prskip:
	s_or_b64 exec, exec, s[12:13]
	s_nop 3
	v_mfma_f32_32x32x16_bf16 v[34:49], v[246:249], v[242:245], v[34:49]
	s_waitcnt lgkmcnt(6)
	v_mfma_f32_32x32x16_bf16 v[50:65], v[222:225], v[146:149], v[50:65]
	s_waitcnt lgkmcnt(4)
	v_mfma_f32_32x32x16_bf16 v[50:65], v[230:233], v[140:143], v[50:65]
	s_waitcnt lgkmcnt(2)
	v_mfma_f32_32x32x16_bf16 v[50:65], v[234:237], v[136:139], v[50:65]
	s_waitcnt lgkmcnt(0)
	s_barrier
	v_mfma_f32_32x32x16_bf16 v[50:65], v[238:241], v[242:245], v[50:65]
	ds_read_b32 v226, v204
	ds_read_b128 v[222:225], v199
	ds_read_b128 v[230:233], v199 offset:16
	ds_read_b32 v227, v205
	ds_read_b128 v[234:237], v214
	ds_read_b128 v[246:249], v214 offset:16
	s_and_saveexec_b64 s[12:13], s[40:41]
	s_cbranch_execz .Lml_nvskip
	ds_read_b32 v134, v201
	s_waitcnt lgkmcnt(0)
	v_fmac_f32_e32 v216, v164, v134
	ds_write_b32 v201, v216
.Lml_nvskip:
	s_or_b64 exec, exec, s[12:13]
	v_lshl_add_u64 v[134:135], s[66:67], 0, v[168:169]
	v_add_co_u32_e32 v136, vcc, s78, v134
	s_add_u32 s8, s8, 4
	s_addc_u32 s9, s9, 0
	v_addc_co_u32_e32 v137, vcc, 0, v135, vcc
	v_add_co_u32_e32 v138, vcc, s79, v134
	s_mov_b64 s[16:17], 0x800
	s_cmp_eq_u32 s14, 1
	v_addc_co_u32_e32 v139, vcc, 0, v135, vcc
	s_waitcnt lgkmcnt(0)
	s_cbranch_scc1 .Lml_nostage
	s_waitcnt vmcnt(10)
	ds_write_b128 v0, v[98:101]
	ds_write_b128 v206, v[102:105] offset:17408
	ds_write_b128 v0, v[106:109] offset:8704
	ds_write_b128 v206, v[110:113] offset:27648
	ds_write_b128 v202, v[114:117] offset:37888
	ds_write_b128 v202, v[118:121] offset:47104
	ds_write_b128 v202, v[122:125] offset:56320
	ds_write_b128 v203, v[126:129] offset:27648
	ds_write_b128 v207, v[130:133]
; #define LAS __attribute__((address_space(3)))
; __device__ __forceinline__ float bflo(unsigned w) { return __uint_as_float(w << 16); }
; __device__ __forceinline__ float bfhi(unsigned w) { return __uint_as_float(w & 0xffff0000u); }
; __device__ __forceinline__ unsigned pk2(float lo, float hi) { return pg8::cvt_pk_bf16(lo, hi); }
; __device__ __forceinline__ void mlstm_seq(LAS unsigned char* lds, int tid_in, int b, int h, const bf16_t* z1, const bf16_t* z2a, const float* g_hnorm, bf16_t* yb, const unsigned char* ws) {
;     ...
;             for (int g = 0; g < 4; ++g) zo[tb][g] = pzo[tb][g];
;         const float wi0 = pwi0, wi1 = pwi1, wq = pwq, eq = peq, dq0 = pdq, dn = pdn;
;     ...
; #pragma unroll
;         for (int tb = 0; tb < 2; ++tb) {
;             const int t = 32 * tb + r;
;             const float inv = INV[t];
;             const f32x4 pa = *(const LAS f32x4*)(PR + t * 8), pb = *(const LAS f32x4*)(PR + t * 8 + 4);
;             const float rn = inv * rsqrtf(inv * inv * ((pa[0] + pa[1]) + (pa[2] + pa[3]) + (pb[0] + pb[1]) + (pb[2] + pb[3])) * (1.f / 256.f) + EPSN);
; #pragma unroll
;             for (int g = 0; g < 4; ++g) {
;                 const int dv = 32 * wid + 8 * g + 4 * hh;
;                 u32x2 w; w.x = pk2(Z[tb][4 * g] * rn * bflo(zo[tb][g].x), Z[tb][4 * g + 1] * rn * bfhi(zo[tb][g].x));
;                 w.y = pk2(Z[tb][4 * g + 2] * rn * bflo(zo[tb][g].y), Z[tb][4 * g + 3] * rn * bfhi(zo[tb][g].y));
;                 *(u32x2*)(yb + (tok0 + t) * Z2_LD + h * 256 + dv) = w;
;             }
;         }
.Lml_nostage:
	s_mov_b64 s[12:13], 0x80000
	v_mul_f32_e32 v140, v226, v226
	v_add_f32_e32 v141, v223, v222
	v_add_f32_e32 v142, v224, v225
	v_add_f32_e32 v143, v232, v233
	v_add_f32_e32 v146, v230, v231
	v_add_f32_e32 v141, v141, v142
	v_add_f32_e32 v141, v141, v146
	v_add_f32_e32 v141, v143, v141
	v_mul_f32_e32 v141, v140, v141
	v_fmamk_f32 v141, v141, 0x3b800000, v221
	v_mul_f32_e32 v142, 0x4b800000, v141
	v_cmp_gt_f32_e32 vcc, s77, v141
	s_nop 1
	v_cndmask_b32_e32 v141, v141, v142, vcc
	v_rsq_f32_e32 v141, v141
	s_nop 0
	v_mul_f32_e32 v142, 0x45800000, v141
	v_cndmask_b32_e32 v141, v141, v142, vcc
	v_mul_f32_e32 v145, v226, v141
	v_mul_f32_e32 v82, v82, v145
	v_lshlrev_b32_e32 v140, 16, v180
	v_mul_f32_e32 v83, v83, v145
	v_and_b32_e32 v141, 0xffff0000, v180
	v_mul_f32_e32 v82, v82, v140
	v_mul_f32_e32 v83, v83, v141
	v_mul_f32_e32 v84, v84, v145
	v_lshlrev_b32_e32 v142, 16, v181
	v_mul_f32_e32 v85, v85, v145
	v_and_b32_e32 v143, 0xffff0000, v181
	v_cvt_pk_bf16_f32 v82, v82, v83
	v_mul_f32_e32 v84, v84, v142
	v_mul_f32_e32 v85, v85, v143
	v_cvt_pk_bf16_f32 v83, v84, v85
	global_store_dwordx2 v[136:137], v[82:83], off
	v_mul_f32_e32 v86, v86, v145
	v_lshlrev_b32_e32 v140, 16, v178
	v_mul_f32_e32 v87, v87, v145
	v_and_b32_e32 v141, 0xffff0000, v178
	v_mul_f32_e32 v86, v86, v140
	v_mul_f32_e32 v87, v87, v141
	v_mul_f32_e32 v88, v88, v145
	v_lshlrev_b32_e32 v142, 16, v179
	v_mul_f32_e32 v89, v89, v145
	v_and_b32_e32 v143, 0xffff0000, v179
	v_cvt_pk_bf16_f32 v86, v86, v87
	v_mul_f32_e32 v88, v88, v142
	v_mul_f32_e32 v89, v89, v143
	v_cvt_pk_bf16_f32 v87, v88, v89
	global_store_dwordx2 v[136:137], v[86:87], off offset:16
	v_mul_f32_e32 v90, v90, v145
	v_lshlrev_b32_e32 v140, 16, v174
	v_mul_f32_e32 v91, v91, v145
	v_and_b32_e32 v141, 0xffff0000, v174
	v_mul_f32_e32 v90, v90, v140
	v_mul_f32_e32 v91, v91, v141
	v_mul_f32_e32 v92, v92, v145
	v_lshlrev_b32_e32 v142, 16, v175
	v_mul_f32_e32 v93, v93, v145
	v_and_b32_e32 v143, 0xffff0000, v175
	v_cvt_pk_bf16_f32 v90, v90, v91
	v_mul_f32_e32 v92, v92, v142
	v_mul_f32_e32 v93, v93, v143
	v_cvt_pk_bf16_f32 v91, v92, v93
	global_store_dwordx2 v[136:137], v[90:91], off offset:32
	v_mul_f32_e32 v94, v94, v145
	v_lshlrev_b32_e32 v140, 16, v166
	v_mul_f32_e32 v95, v95, v145
	v_and_b32_e32 v141, 0xffff0000, v166
	v_mul_f32_e32 v94, v94, v140
	v_mul_f32_e32 v95, v95, v141
	v_mul_f32_e32 v96, v96, v145
	v_lshlrev_b32_e32 v142, 16, v167
	v_mul_f32_e32 v97, v97, v145
	v_and_b32_e32 v143, 0xffff0000, v167
	v_cvt_pk_bf16_f32 v94, v94, v95
	v_mul_f32_e32 v96, v96, v142
	v_mul_f32_e32 v97, v97, v143
	v_cvt_pk_bf16_f32 v95, v96, v97
	global_store_dwordx2 v[136:137], v[94:95], off offset:48
	v_lshl_add_u64 v[150:151], v[150:151], 0, s[12:13]
	v_lshl_add_u64 v[172:173], v[172:173], 0, s[12:13]
	v_lshl_add_u64 v[168:169], v[168:169], 0, s[12:13]
	s_mov_b64 s[12:13], 0x68000
	v_mul_f32_e32 v140, v227, v227
	v_add_f32_e32 v141, v235, v234
	v_add_f32_e32 v142, v236, v237
	v_add_f32_e32 v143, v248, v249
	v_add_f32_e32 v146, v246, v247
	v_add_f32_e32 v141, v141, v142
	v_add_f32_e32 v141, v141, v146
	v_add_f32_e32 v141, v143, v141
	v_mul_f32_e32 v141, v140, v141
	v_fmamk_f32 v141, v141, 0x3b800000, v221
	v_mul_f32_e32 v142, 0x4b800000, v141
	v_cmp_gt_f32_e32 vcc, s77, v141
	s_nop 1
	v_cndmask_b32_e32 v141, v141, v142, vcc
	v_rsq_f32_e32 v141, v141
	s_nop 0
	v_mul_f32_e32 v142, 0x45800000, v141
	v_cndmask_b32_e32 v141, v141, v142, vcc
	v_mul_f32_e32 v145, v227, v141
	v_mul_f32_e32 v66, v66, v145
	v_lshlrev_b32_e32 v140, 16, v158
	v_mul_f32_e32 v67, v67, v145
	v_and_b32_e32 v141, 0xffff0000, v158
	v_mul_f32_e32 v66, v66, v140
	v_mul_f32_e32 v67, v67, v141
	v_mul_f32_e32 v68, v68, v145
	v_lshlrev_b32_e32 v142, 16, v159
	v_mul_f32_e32 v69, v69, v145
	v_and_b32_e32 v143, 0xffff0000, v159
	v_cvt_pk_bf16_f32 v66, v66, v67
	v_mul_f32_e32 v68, v68, v142
	v_mul_f32_e32 v69, v69, v143
	v_cvt_pk_bf16_f32 v67, v68, v69
	global_store_dwordx2 v[138:139], v[66:67], off
	v_mul_f32_e32 v70, v70, v145
	v_lshlrev_b32_e32 v140, 16, v156
	v_mul_f32_e32 v71, v71, v145
	v_and_b32_e32 v141, 0xffff0000, v156
	v_mul_f32_e32 v70, v70, v140
	v_mul_f32_e32 v71, v71, v141
	v_mul_f32_e32 v72, v72, v145
	v_lshlrev_b32_e32 v142, 16, v157
	v_mul_f32_e32 v73, v73, v145
	v_and_b32_e32 v143, 0xffff0000, v157
	v_cvt_pk_bf16_f32 v70, v70, v71
	v_mul_f32_e32 v72, v72, v142
	v_mul_f32_e32 v73, v73, v143
	v_cvt_pk_bf16_f32 v71, v72, v73
	global_store_dwordx2 v[138:139], v[70:71], off offset:16
	v_mul_f32_e32 v74, v74, v145
	v_lshlrev_b32_e32 v140, 16, v154
	v_mul_f32_e32 v75, v75, v145
	v_and_b32_e32 v141, 0xffff0000, v154
	v_mul_f32_e32 v74, v74, v140
	v_mul_f32_e32 v75, v75, v141
	v_mul_f32_e32 v76, v76, v145
	v_lshlrev_b32_e32 v142, 16, v155
	v_mul_f32_e32 v77, v77, v145
	v_and_b32_e32 v143, 0xffff0000, v155
	v_cvt_pk_bf16_f32 v74, v74, v75
	v_mul_f32_e32 v76, v76, v142
	v_mul_f32_e32 v77, v77, v143
	v_cvt_pk_bf16_f32 v75, v76, v77
	global_store_dwordx2 v[138:139], v[74:75], off offset:32
	v_mul_f32_e32 v78, v78, v145
	v_lshlrev_b32_e32 v140, 16, v152
	v_mul_f32_e32 v79, v79, v145
	v_and_b32_e32 v141, 0xffff0000, v152
	v_mul_f32_e32 v78, v78, v140
	v_mul_f32_e32 v79, v79, v141
	v_mul_f32_e32 v80, v80, v145
	v_lshlrev_b32_e32 v142, 16, v153
	v_mul_f32_e32 v81, v81, v145
	v_and_b32_e32 v143, 0xffff0000, v153
	v_cvt_pk_bf16_f32 v78, v78, v79
	v_mul_f32_e32 v80, v80, v142
	v_mul_f32_e32 v81, v81, v143
	v_cvt_pk_bf16_f32 v79, v80, v81
	global_store_dwordx2 v[138:139], v[78:79], off offset:48
	v_lshl_add_u64 v[160:161], v[160:161], 0, s[92:93]
	v_lshl_add_u64 v[162:163], v[162:163], 0, s[94:95]
	v_lshl_add_u64 v[170:171], v[170:171], 0, s[16:17]
	v_lshl_add_u64 v[176:177], v[176:177], 0, s[12:13]
	s_add_i32 s14, s14, -1
	s_waitcnt vmcnt(8)
	v_mov_b64_e32 v[180:181], v[182:183]
	v_mov_b64_e32 v[178:179], v[184:185]
	v_mov_b64_e32 v[174:175], v[186:187]
	v_mov_b64_e32 v[166:167], v[188:189]
	v_mov_b64_e32 v[158:159], v[190:191]
	v_mov_b64_e32 v[156:157], v[192:193]
	v_mov_b64_e32 v[154:155], v[194:195]
	v_mov_b64_e32 v[152:153], v[196:197]
	v_mov_b32_e32 v250, v217
	v_mov_b32_e32 v251, v218
	v_mov_b32_e32 v216, v219
	v_mov_b32_e32 v164, v215
	s_cmp_eq_u32 s14, 0
	s_cbranch_scc1 .LBB0_93
	s_waitcnt lgkmcnt(0)
	s_barrier
	s_branch .Lml_loop
